# P1 K-loop: LDS-DMA addresses from SGPR bases + precomputed lane offsets (22 VALU per K-iteration removed from load segments)
# speedup vs baseline: 1.0080x; 1.0080x over previous
; #define PG8_LAS __attribute__((address_space(3)))
; #define PG8_WAIT_V(n) asm volatile("s_waitcnt vmcnt(" #n ")" ::: "memory")
; #define PG8_BAR __builtin_amdgcn_s_barrier()
; #define S xcd_barrier(bar);
; template <class Epi, bool ALIGN_EPI, bool ABLK = false>
; __device__ __forceinline__ void gemm_phase(PG8_LAS unsigned char* lds, const Gemm g, const StaticOrder& S, const Epi& E) {
;     ...
;     const unsigned ldsw = (unsigned)wid * 1024u;
;     const int aoff = lds_byte(wr * 64 + fr, fq * 8), boff = lds_byte(wc * 32 + fr, fq * 8);
;     ...
;     Unit cur, nxt; int ui = 0;
;     if (!S.next(0, cur)) return;
;     Acc acc;
; #pragma unroll
;     for (int a = 0; a < 2; ++a)
; #pragma unroll
;         for (int b = 0; b < 2; ++b)
; #pragma unroll
;             for (int m = 0; m < 4; ++m)
; #pragma unroll
;                 for (int n = 0; n < 2; ++n) acc[a][b][m][n] = (f32x4){0.f, 0.f, 0.f, 0.f};
;     bf16x8 At[4][2], B0[2][2], B1[2][2];
;     const char* cA = PG8_ABASE(cur); const char* cB = PG8_BBASE(cur);
;     constexpr int RS_MAXT = 12;
;     PG8_LAS float* RS = (PG8_LAS float*)(lds + EX_OFF);
;     f32x4 rq[RS_MAXT][2];
;     if constexpr (Epi::RSTD_LDS) {
; #pragma unroll
;         for (int i = 0; i < RS_MAXT; ++i) { Unit t; if (S.next(i, t)) { const float* p = E.ssqp + (size_t)(t.pm * BM + wid * 32 + (lane & 31)) * 16 + (lane >> 5) * 8; rq[i][0] = *(const f32x4*)p; rq[i][1] = *(const f32x4*)(p + 4); } }
;     }
;     PG8_STAGE(PG8_SB(0, 0), cB, voffB); PG8_STAGE(PG8_SB(0, 1), cB + hstepB, voffB); PG8_STAGE(PG8_SA(0, 0), cA, voffA); PG8_STAGE(PG8_SA(0, 1), cA + hstepA, voffA);
;     if constexpr (Epi::RSTD_LDS) {
;         const int prow = wid * 32 + (lane & 31), slot = (((prow >> 6) & 1) * 16 + (prow & 15)) * 8 + (prow >> 7) * 4 + ((prow >> 4) & 3);
; #pragma unroll
;         for (int i = 0; i < RS_MAXT; ++i) { Unit t; if (S.next(i, t)) {
;             float sm = ((rq[i][0].x + rq[i][0].y) + (rq[i][0].z + rq[i][0].w)) + ((rq[i][1].x + rq[i][1].y) + (rq[i][1].z + rq[i][1].w));
;             sm += __shfl_xor(sm, 32);
;             if (lane < 32) RS[i * 256 + slot] = __builtin_amdgcn_rsqf(sm * (1.0f / D) + EPS); } }
;     }
;     if (wr == 1) PG8_BAR;
;     PG8_WAIT_V(2); PG8_BAR;
;     PG8_STAGE(PG8_SB(1, 0), cB + kstepB, voffB); PG8_STAGE(PG8_SA(1, 0), cA + kstepA, voffA); PG8_STAGE(PG8_SB(1, 1), cB + hstepB + kstepB, voffB);
;     PG8_WAIT_V(6); PG8_BAR;
.LBB0_396:
	s_and_b32 s5, s30, 3
	v_and_b32_e32 v8, 15, v0
	v_and_b32_e32 v9, 48, v0
	v_lshlrev_b32_e32 v11, 2, v0
	v_lshlrev_b32_e32 v13, 6, v0
	s_movk_i32 s29, 0x3c0
	v_lshl_or_b32 v10, v8, 6, v9
	v_and_b32_e32 v11, 32, v11
	s_lshl_b32 s28, s5, 12
	v_and_or_b32 v9, v13, s29, v9
	v_bitop3_b32 v180, s28, v9, v11 bitop3:0xf6
	s_mov_b64 s[28:29], 0x80
	s_add_i32 m0, s55, 0x18000
	v_lshl_add_u64 v[2:3], v[2:3], 0, s[28:29]
	s_lshl_b32 s38, s4, 13
	s_lshl_b32 s17, s5, 5
	s_waitcnt vmcnt(2)
	s_barrier
	global_load_lds_dwordx4 v[2:3], off
	v_lshl_add_u64 v[2:3], v[4:5], 0, s[28:29]
	s_add_i32 m0, s55, 0x1a000
	s_mov_b64 s[30:31], 0x8000
	s_add_i32 s59, s55, 0x8000
	s_add_i32 s61, s55, 0xa000
	global_load_lds_dwordx4 v[2:3], off
	v_lshl_add_u64 v[2:3], v[100:101], 0, s[30:31]
	s_mov_b32 m0, s59
	s_mov_b64 s[34:35], 0xa000
	s_add_u32 s36, s22, 0x40080
	global_load_lds_dwordx4 v[2:3], off
	v_lshl_add_u64 v[2:3], v[100:101], 0, s[34:35]
	s_mov_b32 m0, s61
	s_addc_u32 s37, s23, 0
	global_load_lds_dwordx4 v[2:3], off
	s_add_i32 m0, s55, 0x1c000
	v_lshl_add_u64 v[2:3], s[36:37], 0, v[148:149]
	global_load_lds_dwordx4 v[2:3], off
	v_lshl_add_u64 v[2:3], s[36:37], 0, v[150:151]
	s_add_i32 m0, s55, 0x1e000
	s_cmpk_lt_u32 s33, 0x100
	global_load_lds_dwordx4 v[2:3], off
	v_and_b32_e32 v2, 12, v99
	v_lshlrev_b32_e32 v152, 2, v2
	v_mov_b32_e32 v153, 0
	s_cselect_b64 s[36:37], -1, 0
	v_lshl_add_u64 v[154:155], s[6:7], 0, v[152:153]
	s_lshl_b32 s6, s4, 9
	s_add_i32 s6, s6, 0
	v_lshl_or_b32 v179, s4, 6, v8
	s_add_i32 s6, s6, 0x20000
	s_lshl_b32 s4, s4, 3
	v_lshl_add_u32 v181, v8, 5, s6
	s_bfe_u32 s6, s33, 0x10006
	s_and_b32 s4, s4, 8
	s_or_b32 s6, s4, s6
	s_or_b32 s4, s4, s5
	s_lshl_b32 s4, s4, 10
	v_bitop3_b32 v2, v10, s4, v11 bitop3:0xde
	v_or_b32_e32 v156, 0x800, v2
	v_or_b32_e32 v160, 0x1800, v2
	v_xor_b32_e32 v2, 16, v6
	s_waitcnt vmcnt(6)
	s_lshl_b32 s6, s6, 10
	v_cmp_lt_i32_e32 vcc, v2, v7
	v_bitop3_b32 v12, v10, s38, v11 bitop3:0xde
	s_and_b32 s62, s38, 0x4000
	v_bitop3_b32 v152, v10, s6, v11 bitop3:0xde
	v_cndmask_b32_e32 v2, v6, v2, vcc
	s_mov_b32 s60, 0
	v_mov_b32_e32 v157, v153
	v_or_b32_e32 v158, 0x1000, v152
	v_mov_b32_e32 v159, v153
	v_mov_b32_e32 v161, v153
	s_xor_b32 s63, s62, 0x4000
	v_lshlrev_b32_e32 v182, 2, v2
	s_add_i32 s64, 0, 0x10000
	s_add_i32 s65, 0, 0x14000
	v_add_u32_e32 v244, 0x2000, v146
	v_add_u32_e32 v245, 0x4000, v146
	v_add_u32_e32 v246, 0x6000, v146
	v_add_u32_e32 v247, 0x8000, v146
	v_add_u32_e32 v248, 0xa000, v146
	v_add_u32_e32 v249, 0xc000, v146
	v_add_u32_e32 v250, 0xe000, v146
	v_add_u32_e32 v251, 0x10000, v180
	v_add_u32_e32 v183, 0, v12
	v_mov_b32_e32 v2, v153
	v_mov_b32_e32 v3, v153
	v_mov_b32_e32 v4, v153
	v_mov_b32_e32 v5, v153
	v_mov_b32_e32 v6, v153
	v_mov_b32_e32 v7, v153
	v_mov_b32_e32 v8, v153
	v_mov_b32_e32 v9, v153
	v_mov_b32_e32 v10, v153
	v_mov_b32_e32 v11, v153
	v_mov_b32_e32 v12, v153
	v_mov_b32_e32 v13, v153
	v_mov_b32_e32 v14, v153
	v_mov_b32_e32 v15, v153
	v_mov_b32_e32 v16, v153
	v_mov_b32_e32 v17, v153
	v_mov_b32_e32 v18, v153
	v_mov_b32_e32 v19, v153
	v_mov_b32_e32 v20, v153
	v_mov_b32_e32 v21, v153
	v_mov_b32_e32 v22, v153
	v_mov_b32_e32 v23, v153
	v_mov_b32_e32 v24, v153
	v_mov_b32_e32 v25, v153
	v_mov_b32_e32 v26, v153
	v_mov_b32_e32 v27, v153
	v_mov_b32_e32 v28, v153
	v_mov_b32_e32 v29, v153
	v_mov_b32_e32 v30, v153
	v_mov_b32_e32 v31, v153
	v_mov_b32_e32 v32, v153
	v_mov_b32_e32 v33, v153
	v_mov_b32_e32 v34, v153
	v_mov_b32_e32 v35, v153
	v_mov_b32_e32 v36, v153
	v_mov_b32_e32 v37, v153
	v_mov_b32_e32 v38, v153
	v_mov_b32_e32 v39, v153
	v_mov_b32_e32 v40, v153
	v_mov_b32_e32 v41, v153
	v_mov_b32_e32 v42, v153
	v_mov_b32_e32 v43, v153
	v_mov_b32_e32 v44, v153
	v_mov_b32_e32 v45, v153
	v_mov_b32_e32 v46, v153
	v_mov_b32_e32 v47, v153
	v_mov_b32_e32 v48, v153
	v_mov_b32_e32 v49, v153
	v_mov_b32_e32 v50, v153
	v_mov_b32_e32 v51, v153
	v_mov_b32_e32 v52, v153
	v_mov_b32_e32 v53, v153
	v_mov_b32_e32 v54, v153
	v_mov_b32_e32 v55, v153
	v_mov_b32_e32 v56, v153
	v_mov_b32_e32 v57, v153
	v_mov_b32_e32 v58, v153
	v_mov_b32_e32 v59, v153
	v_mov_b32_e32 v60, v153
	v_mov_b32_e32 v61, v153
	v_mov_b32_e32 v62, v153
	v_mov_b32_e32 v63, v153
	v_mov_b32_e32 v64, v153
	v_mov_b32_e32 v65, v153
	v_mov_b32_e32 v66, v153
	v_mov_b32_e32 v67, v153
	v_mov_b32_e32 v68, v153
	v_mov_b32_e32 v69, v153
	v_mov_b32_e32 v70, v153
	v_mov_b32_e32 v71, v153
	v_mov_b32_e32 v72, v153
	v_mov_b32_e32 v73, v153
	v_mov_b32_e32 v74, v153
	v_mov_b32_e32 v75, v153
	v_mov_b32_e32 v76, v153
	v_mov_b32_e32 v77, v153
	v_mov_b32_e32 v78, v153
	v_mov_b32_e32 v79, v153
	v_mov_b32_e32 v80, v153
	v_mov_b32_e32 v81, v153
	v_mov_b32_e32 v82, v153
	v_mov_b32_e32 v83, v153
	v_mov_b32_e32 v84, v153
	v_mov_b32_e32 v85, v153
	v_mov_b32_e32 v86, v153
	v_mov_b32_e32 v87, v153
	v_mov_b32_e32 v88, v153
	v_mov_b32_e32 v89, v153
	v_mov_b32_e32 v90, v153
	v_mov_b32_e32 v91, v153
	v_mov_b32_e32 v92, v153
	v_mov_b32_e32 v93, v153
	v_mov_b32_e32 v94, v153
	v_mov_b32_e32 v95, v153
	v_mov_b32_e32 v96, v153
	v_mov_b32_e32 v97, v153
	v_mov_b32_e32 v98, v153
	v_mov_b32_e32 v99, v153
	v_mov_b32_e32 v100, v153
	v_mov_b32_e32 v101, v153
	v_mov_b32_e32 v102, v153
	v_mov_b32_e32 v103, v153
	v_mov_b32_e32 v104, v153
	v_mov_b32_e32 v105, v153
	v_mov_b32_e32 v106, v153
	v_mov_b32_e32 v107, v153
	v_mov_b32_e32 v108, v153
	v_mov_b32_e32 v109, v153
	v_mov_b32_e32 v110, v153
	v_mov_b32_e32 v111, v153
	v_mov_b32_e32 v112, v153
	v_mov_b32_e32 v113, v153
	v_mov_b32_e32 v114, v153
	v_mov_b32_e32 v115, v153
	v_mov_b32_e32 v116, v153
	v_mov_b32_e32 v117, v153
	v_mov_b32_e32 v118, v153
	v_mov_b32_e32 v119, v153
	v_mov_b32_e32 v120, v153
	v_mov_b32_e32 v121, v153
	v_mov_b32_e32 v122, v153
	v_mov_b32_e32 v123, v153
	v_mov_b32_e32 v124, v153
	v_mov_b32_e32 v125, v153
	v_mov_b32_e32 v126, v153
	v_mov_b32_e32 v127, v153
	v_mov_b32_e32 v128, v153
	v_mov_b32_e32 v129, v153
	v_mov_b32_e32 v184, 0x358637bd
	v_mov_b64_e32 v[162:163], 0xb00
	v_mov_b64_e32 v[164:165], 0xaff
	s_barrier
	s_branch .LBB0_399

; #define PG8_STAGE(bufoff, gbase, voff) do { _Pragma("unroll") for (int _i = 0; _i < 2; ++_i) \
;         __builtin_amdgcn_global_load_lds((const unsigned*)((const char*)(gbase) + (voff)[_i]), (PG8_LAS unsigned*)(lds + (bufoff) + ldsw + _i * 8192), 16, 0, 0); } while (0)
; #define PG8_LDA(dst, b, h) do { _Pragma("unroll") for (int m = 0; m < 4; ++m) _Pragma("unroll") for (int k = 0; k < 2; ++k) dst[m][k] = *(const PG8_LAS bf16x8*)(lds + PG8_SA(b, h) + aoff + m * 2048 + k * 1024); } while (0)
; #define PG8_LDB(dst, b, h) do { _Pragma("unroll") for (int n = 0; n < 2; ++n) _Pragma("unroll") for (int k = 0; k < 2; ++k) dst[n][k] = *(const PG8_LAS bf16x8*)(lds + PG8_SB(b, h) + boff + n * 2048 + k * 1024); } while (0)
; #define PG8_MMA(ai, bj, At, Bt) do { __builtin_amdgcn_s_setprio(1); _Pragma("unroll") for (int m = 0; m < 4; ++m) _Pragma("unroll") for (int n = 0; n < 2; ++n) _Pragma("unroll") for (int k = 0; k < 2; ++k) \
;         acc[ai][bj][m][n] = __builtin_amdgcn_mfma_f32_16x16x32_bf16(Bt[n][k], At[m][k], acc[ai][bj][m][n], 0, 0, 0); __builtin_amdgcn_s_setprio(0); } while (0)
; #define PG8_BAR __builtin_amdgcn_s_barrier()
; template <class Epi, bool ALIGN_EPI, bool ABLK = false>
; __device__ __forceinline__ void gemm_phase(PG8_LAS unsigned char* lds, const Gemm g, const StaticOrder& S, const Epi& E) {
;     ...
;     for (;;) {
;         const bool has_next = S.next(ui + 1, nxt);
;         const char* nA = has_next ? PG8_ABASE(nxt) : cA; const char* nB = has_next ? PG8_BBASE(nxt) : cB;
;         for (int t = 0; t < nt; t += 2) {
;             const bool last = (t == nt - 2);
;             const char* a1 = cA + (size_t)(t + 1) * kstepA;
;             const char* a2 = last ? nA : cA + (size_t)(t + 2) * kstepA; const char* b2 = last ? nB : cB + (size_t)(t + 2) * kstepB;
;             const char* a3 = a2 + kstepA; const char* b3 = b2 + kstepB;
;             PG8_LDB(B0, 0, 0); PG8_LDB(B1, 0, 1); PG8_SCHED; PG8_LDA(At, 0, 0); PG8_STAGE(PG8_SA(1, 1), a1 + hstepA, voffA);
;             PG8_WAIT_V(8); PG8_WAIT_L(0); PG8_BAR; PG8_MMA(0, 0, At, B0); PG8_MMA(0, 1, At, B1); PG8_BAR; PG8_SCHED;
;             PG8_LDA(At, 0, 1); PG8_STAGE(PG8_SB(0, 0), b2, voffB); PG8_STAGE(PG8_SB(0, 1), b2 + hstepB, voffB); PG8_STAGE(PG8_SA(0, 0), a2, voffA);
;             PG8_WAIT_V(8); PG8_WAIT_L(0); PG8_BAR; PG8_MMA(1, 0, At, B0); PG8_MMA(1, 1, At, B1); PG8_BAR; PG8_SCHED;
.LBB0_401:
	s_ashr_i32 s41, s40, 31
	s_lshl_b64 s[42:43], s[40:41], 19
	s_add_u32 s42, s11, s42
	s_addc_u32 s43, s54, s43
	s_and_b64 s[44:45], s[6:7], exec
	s_cselect_b32 s41, s43, s25
	s_cselect_b32 s66, s42, s24
	s_ashr_i32 s39, s38, 31
	s_lshl_b64 s[44:45], s[38:39], 19
	s_add_u32 s44, s12, s44
	s_addc_u32 s45, s13, s45
	s_and_b64 s[46:47], s[6:7], exec
	s_cselect_b32 s39, s45, s23
	s_cselect_b32 s67, s44, s22
	s_add_u32 s68, s22, 0x100
	s_addc_u32 s69, s23, 0
	s_mov_b32 s70, -2
	s_mov_b64 s[46:47], 0x10000
	s_mov_b64 s[82:83], s[24:25]
.LBB0_402:
	ds_read_b128 v[132:135], v251
	ds_read_b128 v[136:139], v251 offset:1024
	ds_read_b128 v[140:143], v251 offset:2048
	ds_read_b128 v[186:189], v251 offset:3072
	ds_read_b128 v[190:193], v251 offset:16384
	ds_read_b128 v[194:197], v251 offset:17408
	ds_read_b128 v[198:201], v251 offset:18432
	ds_read_b128 v[202:205], v251 offset:19456
	s_add_u32 s48, s24, s46
	s_addc_u32 s49, s25, s47
	s_cmp_eq_u32 s70, 12
	s_cselect_b32 s85, s41, s49
	s_cselect_b32 s84, s66, s48
	s_cselect_b32 s49, s39, s69
	s_cselect_b32 s48, s67, s68
	s_mov_b64 s[74:75], 0xc000
	s_add_i32 m0, s55, 0xc000
	s_mov_b64 s[74:75], 0xe000
	ds_read_b128 v[206:209], v183
	ds_read_b128 v[210:213], v183 offset:1024
	ds_read_b128 v[214:217], v183 offset:2048
	ds_read_b128 v[218:221], v183 offset:3072
	ds_read_b128 v[222:225], v183 offset:4096
	ds_read_b128 v[226:229], v183 offset:5120
	ds_read_b128 v[230:233], v183 offset:6144
	ds_read_b128 v[234:237], v183 offset:7168
	global_load_lds_dwordx4 v249, s[82:83]
	s_add_i32 m0, s55, 0xe000
	s_nop 0
	global_load_lds_dwordx4 v250, s[82:83]
	s_waitcnt vmcnt(8)
	s_waitcnt lgkmcnt(0)
	s_barrier
	s_setprio 1
	s_waitcnt lgkmcnt(0)
	v_mfma_f32_16x16x32_bf16 v[126:129], v[132:135], v[206:209], v[126:129]
	v_mfma_f32_16x16x32_bf16 v[122:125], v[140:143], v[206:209], v[122:125]
	v_mfma_f32_16x16x32_bf16 v[118:121], v[132:135], v[214:217], v[118:121]
	v_mfma_f32_16x16x32_bf16 v[114:117], v[140:143], v[214:217], v[114:117]
	v_mfma_f32_16x16x32_bf16 v[110:113], v[132:135], v[222:225], v[110:113]
	v_mfma_f32_16x16x32_bf16 v[106:109], v[140:143], v[222:225], v[106:109]
	v_mfma_f32_16x16x32_bf16 v[102:105], v[132:135], v[230:233], v[102:105]
	v_mfma_f32_16x16x32_bf16 v[98:101], v[140:143], v[230:233], v[98:101]
	v_mfma_f32_16x16x32_bf16 v[126:129], v[136:139], v[210:213], v[126:129]
	v_mfma_f32_16x16x32_bf16 v[122:125], v[186:189], v[210:213], v[122:125]
	v_mfma_f32_16x16x32_bf16 v[118:121], v[136:139], v[218:221], v[118:121]
	v_mfma_f32_16x16x32_bf16 v[114:117], v[186:189], v[218:221], v[114:117]
	v_mfma_f32_16x16x32_bf16 v[110:113], v[136:139], v[226:229], v[110:113]
	v_mfma_f32_16x16x32_bf16 v[106:109], v[186:189], v[226:229], v[106:109]
	v_mfma_f32_16x16x32_bf16 v[102:105], v[136:139], v[234:237], v[102:105]
	v_mfma_f32_16x16x32_bf16 v[98:101], v[186:189], v[234:237], v[98:101]
	s_setprio 0
	s_setprio 1
	v_mfma_f32_16x16x32_bf16 v[94:97], v[190:193], v[206:209], v[94:97]
	v_mfma_f32_16x16x32_bf16 v[90:93], v[198:201], v[206:209], v[90:93]
	v_mfma_f32_16x16x32_bf16 v[86:89], v[190:193], v[214:217], v[86:89]
	v_mfma_f32_16x16x32_bf16 v[82:85], v[198:201], v[214:217], v[82:85]
	v_mfma_f32_16x16x32_bf16 v[78:81], v[190:193], v[222:225], v[78:81]
	v_mfma_f32_16x16x32_bf16 v[74:77], v[198:201], v[222:225], v[74:77]
	v_mfma_f32_16x16x32_bf16 v[70:73], v[190:193], v[230:233], v[70:73]
	v_mfma_f32_16x16x32_bf16 v[66:69], v[198:201], v[230:233], v[66:69]
	v_mfma_f32_16x16x32_bf16 v[94:97], v[194:197], v[210:213], v[94:97]
	v_mfma_f32_16x16x32_bf16 v[90:93], v[202:205], v[210:213], v[90:93]
	v_mfma_f32_16x16x32_bf16 v[86:89], v[194:197], v[218:221], v[86:89]
	v_mfma_f32_16x16x32_bf16 v[82:85], v[202:205], v[218:221], v[82:85]
	v_mfma_f32_16x16x32_bf16 v[78:81], v[194:197], v[226:229], v[78:81]
	v_mfma_f32_16x16x32_bf16 v[74:77], v[202:205], v[226:229], v[74:77]
	v_mfma_f32_16x16x32_bf16 v[70:73], v[194:197], v[234:237], v[70:73]
	v_mfma_f32_16x16x32_bf16 v[66:69], v[202:205], v[234:237], v[66:69]
	s_setprio 0
	s_barrier
	s_add_i32 s71, s64, s9
	s_mov_b32 m0, s71
	ds_read_b128 v[206:209], v183 offset:16384
	ds_read_b128 v[210:213], v183 offset:17408
	ds_read_b128 v[214:217], v183 offset:18432
	ds_read_b128 v[218:221], v183 offset:19456
	ds_read_b128 v[222:225], v183 offset:20480
	ds_read_b128 v[226:229], v183 offset:21504
	ds_read_b128 v[230:233], v183 offset:22528
	ds_read_b128 v[234:237], v183 offset:23552
	global_load_lds_dwordx4 v148, s[48:49]
	s_add_i32 m0, s71, 0x2000
	s_add_u32 s74, s48, 0x40000
	s_addc_u32 s75, s49, 0
	s_add_i32 s71, s65, s9
	global_load_lds_dwordx4 v150, s[48:49]
	s_mov_b32 m0, s71
	s_nop 0
	global_load_lds_dwordx4 v148, s[74:75]
	s_add_i32 m0, s71, 0x2000
	s_nop 0
	global_load_lds_dwordx4 v150, s[74:75]
	s_mov_b32 m0, s55
	s_mov_b64 s[72:73], 0x2000
	global_load_lds_dwordx4 v146, s[84:85]
	s_mov_b32 m0, s56
	s_nop 0
	global_load_lds_dwordx4 v244, s[84:85]
	s_waitcnt vmcnt(8)
	s_waitcnt lgkmcnt(0)
	s_barrier
; #define PG8_STAGE(bufoff, gbase, voff) do { _Pragma("unroll") for (int _i = 0; _i < 2; ++_i) \
;         __builtin_amdgcn_global_load_lds((const unsigned*)((const char*)(gbase) + (voff)[_i]), (PG8_LAS unsigned*)(lds + (bufoff) + ldsw + _i * 8192), 16, 0, 0); } while (0)
; #define PG8_LDA(dst, b, h) do { _Pragma("unroll") for (int m = 0; m < 4; ++m) _Pragma("unroll") for (int k = 0; k < 2; ++k) dst[m][k] = *(const PG8_LAS bf16x8*)(lds + PG8_SA(b, h) + aoff + m * 2048 + k * 1024); } while (0)
; #define PG8_LDB(dst, b, h) do { _Pragma("unroll") for (int n = 0; n < 2; ++n) _Pragma("unroll") for (int k = 0; k < 2; ++k) dst[n][k] = *(const PG8_LAS bf16x8*)(lds + PG8_SB(b, h) + boff + n * 2048 + k * 1024); } while (0)
; #define PG8_MMA(ai, bj, At, Bt) do { __builtin_amdgcn_s_setprio(1); _Pragma("unroll") for (int m = 0; m < 4; ++m) _Pragma("unroll") for (int n = 0; n < 2; ++n) _Pragma("unroll") for (int k = 0; k < 2; ++k) \
;         acc[ai][bj][m][n] = __builtin_amdgcn_mfma_f32_16x16x32_bf16(Bt[n][k], At[m][k], acc[ai][bj][m][n], 0, 0, 0); __builtin_amdgcn_s_setprio(0); } while (0)
; #define PG8_WAIT_V(n) asm volatile("s_waitcnt vmcnt(" #n ")" ::: "memory")
; #define PG8_WAIT_L(n) asm volatile("s_waitcnt lgkmcnt(" #n ")" ::: "memory")
; #define PG8_BAR __builtin_amdgcn_s_barrier()
; #define PG8_SCHED __builtin_amdgcn_sched_barrier(0)
; template <class Epi, bool ALIGN_EPI, bool ABLK = false>
; __device__ __forceinline__ void gemm_phase(PG8_LAS unsigned char* lds, const Gemm g, const StaticOrder& S, const Epi& E) {
;     ...
;             PG8_WAIT_V(8); PG8_WAIT_L(0); PG8_BAR; PG8_MMA(1, 0, At, B0); PG8_MMA(1, 1, At, B1); PG8_BAR; PG8_SCHED;
;             PG8_LDB(B0, 1, 0); PG8_LDB(B1, 1, 1); PG8_SCHED; PG8_LDA(At, 1, 0); PG8_STAGE(PG8_SA(0, 1), a2 + hstepA, voffA);
;             PG8_WAIT_V(8); PG8_WAIT_L(0); PG8_BAR; PG8_MMA(0, 0, At, B0); PG8_MMA(0, 1, At, B1); PG8_BAR; PG8_SCHED;
	s_setprio 1
	s_waitcnt lgkmcnt(0)
	v_mfma_f32_16x16x32_bf16 v[62:65], v[132:135], v[206:209], v[62:65]
	v_mfma_f32_16x16x32_bf16 v[58:61], v[140:143], v[206:209], v[58:61]
	v_mfma_f32_16x16x32_bf16 v[54:57], v[132:135], v[214:217], v[54:57]
	v_mfma_f32_16x16x32_bf16 v[50:53], v[140:143], v[214:217], v[50:53]
	v_mfma_f32_16x16x32_bf16 v[46:49], v[132:135], v[222:225], v[46:49]
	v_mfma_f32_16x16x32_bf16 v[42:45], v[140:143], v[222:225], v[42:45]
	v_mfma_f32_16x16x32_bf16 v[38:41], v[132:135], v[230:233], v[38:41]
	v_mfma_f32_16x16x32_bf16 v[34:37], v[140:143], v[230:233], v[34:37]
	v_mfma_f32_16x16x32_bf16 v[62:65], v[136:139], v[210:213], v[62:65]
	v_mfma_f32_16x16x32_bf16 v[58:61], v[186:189], v[210:213], v[58:61]
	v_mfma_f32_16x16x32_bf16 v[54:57], v[136:139], v[218:221], v[54:57]
	v_mfma_f32_16x16x32_bf16 v[50:53], v[186:189], v[218:221], v[50:53]
	v_mfma_f32_16x16x32_bf16 v[46:49], v[136:139], v[226:229], v[46:49]
	v_mfma_f32_16x16x32_bf16 v[42:45], v[186:189], v[226:229], v[42:45]
	v_mfma_f32_16x16x32_bf16 v[38:41], v[136:139], v[234:237], v[38:41]
	v_mfma_f32_16x16x32_bf16 v[34:37], v[186:189], v[234:237], v[34:37]
	s_setprio 0
	s_setprio 1
	v_mfma_f32_16x16x32_bf16 v[30:33], v[190:193], v[206:209], v[30:33]
	v_mfma_f32_16x16x32_bf16 v[26:29], v[198:201], v[206:209], v[26:29]
	v_mfma_f32_16x16x32_bf16 v[22:25], v[190:193], v[214:217], v[22:25]
	v_mfma_f32_16x16x32_bf16 v[18:21], v[198:201], v[214:217], v[18:21]
	v_mfma_f32_16x16x32_bf16 v[14:17], v[190:193], v[222:225], v[14:17]
	v_mfma_f32_16x16x32_bf16 v[10:13], v[198:201], v[222:225], v[10:13]
	v_mfma_f32_16x16x32_bf16 v[6:9], v[190:193], v[230:233], v[6:9]
	v_mfma_f32_16x16x32_bf16 v[2:5], v[198:201], v[230:233], v[2:5]
	v_mfma_f32_16x16x32_bf16 v[30:33], v[194:197], v[210:213], v[30:33]
	v_mfma_f32_16x16x32_bf16 v[26:29], v[202:205], v[210:213], v[26:29]
	v_mfma_f32_16x16x32_bf16 v[22:25], v[194:197], v[218:221], v[22:25]
	v_mfma_f32_16x16x32_bf16 v[18:21], v[202:205], v[218:221], v[18:21]
	v_mfma_f32_16x16x32_bf16 v[14:17], v[194:197], v[226:229], v[14:17]
	v_mfma_f32_16x16x32_bf16 v[10:13], v[202:205], v[226:229], v[10:13]
	v_mfma_f32_16x16x32_bf16 v[6:9], v[194:197], v[234:237], v[6:9]
	v_mfma_f32_16x16x32_bf16 v[2:5], v[202:205], v[234:237], v[2:5]
	s_setprio 0
	s_barrier
	s_add_i32 s71, 0, 0x18000
	s_add_i32 s74, 0, 0x1c000
	ds_read_b128 v[132:135], v251 offset:32768
	ds_read_b128 v[136:139], v251 offset:33792
	ds_read_b128 v[140:143], v251 offset:34816
	ds_read_b128 v[186:189], v251 offset:35840
	ds_read_b128 v[190:193], v251 offset:49152
	ds_read_b128 v[194:197], v251 offset:50176
	ds_read_b128 v[198:201], v251 offset:51200
	ds_read_b128 v[202:205], v251 offset:52224
	s_mov_b64 s[72:73], 0x4000
	s_mov_b32 m0, s57
	s_mov_b64 s[72:73], 0x6000
	ds_read_b128 v[206:209], v183 offset:32768
	ds_read_b128 v[210:213], v183 offset:33792
	ds_read_b128 v[214:217], v183 offset:34816
	ds_read_b128 v[218:221], v183 offset:35840
	ds_read_b128 v[222:225], v183 offset:36864
	ds_read_b128 v[226:229], v183 offset:37888
	ds_read_b128 v[230:233], v183 offset:38912
	ds_read_b128 v[234:237], v183 offset:39936
	global_load_lds_dwordx4 v245, s[84:85]
	s_mov_b32 m0, s58
	s_nop 0
	global_load_lds_dwordx4 v246, s[84:85]
	s_waitcnt vmcnt(8)
	s_waitcnt lgkmcnt(0)
	s_barrier
	s_setprio 1
	s_waitcnt lgkmcnt(0)
	v_mfma_f32_16x16x32_bf16 v[126:129], v[132:135], v[206:209], v[126:129]
	v_mfma_f32_16x16x32_bf16 v[122:125], v[140:143], v[206:209], v[122:125]
	v_mfma_f32_16x16x32_bf16 v[118:121], v[132:135], v[214:217], v[118:121]
	v_mfma_f32_16x16x32_bf16 v[114:117], v[140:143], v[214:217], v[114:117]
	v_mfma_f32_16x16x32_bf16 v[110:113], v[132:135], v[222:225], v[110:113]
	v_mfma_f32_16x16x32_bf16 v[106:109], v[140:143], v[222:225], v[106:109]
	v_mfma_f32_16x16x32_bf16 v[102:105], v[132:135], v[230:233], v[102:105]
	v_mfma_f32_16x16x32_bf16 v[98:101], v[140:143], v[230:233], v[98:101]
	v_mfma_f32_16x16x32_bf16 v[126:129], v[136:139], v[210:213], v[126:129]
	v_mfma_f32_16x16x32_bf16 v[122:125], v[186:189], v[210:213], v[122:125]
	v_mfma_f32_16x16x32_bf16 v[118:121], v[136:139], v[218:221], v[118:121]
	v_mfma_f32_16x16x32_bf16 v[114:117], v[186:189], v[218:221], v[114:117]
	v_mfma_f32_16x16x32_bf16 v[110:113], v[136:139], v[226:229], v[110:113]
	v_mfma_f32_16x16x32_bf16 v[106:109], v[186:189], v[226:229], v[106:109]
	v_mfma_f32_16x16x32_bf16 v[102:105], v[136:139], v[234:237], v[102:105]
	v_mfma_f32_16x16x32_bf16 v[98:101], v[186:189], v[234:237], v[98:101]
	s_setprio 0
	s_setprio 1
	v_mfma_f32_16x16x32_bf16 v[94:97], v[190:193], v[206:209], v[94:97]
	v_mfma_f32_16x16x32_bf16 v[90:93], v[198:201], v[206:209], v[90:93]
	v_mfma_f32_16x16x32_bf16 v[86:89], v[190:193], v[214:217], v[86:89]
	v_mfma_f32_16x16x32_bf16 v[82:85], v[198:201], v[214:217], v[82:85]
	v_mfma_f32_16x16x32_bf16 v[78:81], v[190:193], v[222:225], v[78:81]
	v_mfma_f32_16x16x32_bf16 v[74:77], v[198:201], v[222:225], v[74:77]
	v_mfma_f32_16x16x32_bf16 v[70:73], v[190:193], v[230:233], v[70:73]
	v_mfma_f32_16x16x32_bf16 v[66:69], v[198:201], v[230:233], v[66:69]
	v_mfma_f32_16x16x32_bf16 v[94:97], v[194:197], v[210:213], v[94:97]
	v_mfma_f32_16x16x32_bf16 v[90:93], v[202:205], v[210:213], v[90:93]
	v_mfma_f32_16x16x32_bf16 v[86:89], v[194:197], v[218:221], v[86:89]
	v_mfma_f32_16x16x32_bf16 v[82:85], v[202:205], v[218:221], v[82:85]
	v_mfma_f32_16x16x32_bf16 v[78:81], v[194:197], v[226:229], v[78:81]
	v_mfma_f32_16x16x32_bf16 v[74:77], v[202:205], v[226:229], v[74:77]
	v_mfma_f32_16x16x32_bf16 v[70:73], v[194:197], v[234:237], v[70:73]
	v_mfma_f32_16x16x32_bf16 v[66:69], v[202:205], v[234:237], v[66:69]
	s_setprio 0
	s_barrier
; #define PG8_STAGE(bufoff, gbase, voff) do { _Pragma("unroll") for (int _i = 0; _i < 2; ++_i) \
;         __builtin_amdgcn_global_load_lds((const unsigned*)((const char*)(gbase) + (voff)[_i]), (PG8_LAS unsigned*)(lds + (bufoff) + ldsw + _i * 8192), 16, 0, 0); } while (0)
; #define PG8_LDA(dst, b, h) do { _Pragma("unroll") for (int m = 0; m < 4; ++m) _Pragma("unroll") for (int k = 0; k < 2; ++k) dst[m][k] = *(const PG8_LAS bf16x8*)(lds + PG8_SA(b, h) + aoff + m * 2048 + k * 1024); } while (0)
; #define PG8_MMA(ai, bj, At, Bt) do { __builtin_amdgcn_s_setprio(1); _Pragma("unroll") for (int m = 0; m < 4; ++m) _Pragma("unroll") for (int n = 0; n < 2; ++n) _Pragma("unroll") for (int k = 0; k < 2; ++k) \
;         acc[ai][bj][m][n] = __builtin_amdgcn_mfma_f32_16x16x32_bf16(Bt[n][k], At[m][k], acc[ai][bj][m][n], 0, 0, 0); __builtin_amdgcn_s_setprio(0); } while (0)
; #define PG8_WAIT_V(n) asm volatile("s_waitcnt vmcnt(" #n ")" ::: "memory")
; #define PG8_WAIT_L(n) asm volatile("s_waitcnt lgkmcnt(" #n ")" ::: "memory")
; #define PG8_BAR __builtin_amdgcn_s_barrier()
; #define PG8_SCHED __builtin_amdgcn_sched_barrier(0)
; template <class Epi, bool ALIGN_EPI, bool ABLK = false>
; __device__ __forceinline__ void gemm_phase(PG8_LAS unsigned char* lds, const Gemm g, const StaticOrder& S, const Epi& E) {
;     ...
;         for (int t = 0; t < nt; t += 2) {
;     ...
;             PG8_LDA(At, 1, 1); PG8_STAGE(PG8_SB(1, 0), b3, voffB); PG8_STAGE(PG8_SB(1, 1), b3 + hstepB, voffB); PG8_STAGE(PG8_SA(1, 0), a3, voffA);
;             PG8_WAIT_V(8); PG8_WAIT_L(0); PG8_BAR; PG8_MMA(1, 0, At, B0); PG8_MMA(1, 1, At, B1); PG8_BAR; PG8_SCHED;
;         }
	s_add_i32 s71, s71, s9
	s_add_u32 s86, s48, s28
	s_addc_u32 s87, s49, s29
	s_mov_b32 m0, s71
	ds_read_b128 v[206:209], v183 offset:49152
	ds_read_b128 v[210:213], v183 offset:50176
	ds_read_b128 v[214:217], v183 offset:51200
	ds_read_b128 v[218:221], v183 offset:52224
	ds_read_b128 v[222:225], v183 offset:53248
	ds_read_b128 v[226:229], v183 offset:54272
	ds_read_b128 v[230:233], v183 offset:55296
	ds_read_b128 v[234:237], v183 offset:56320
	global_load_lds_dwordx4 v148, s[86:87]
	s_add_i32 m0, s71, 0x2000
	s_add_u32 s48, s48, 0x40080
	s_addc_u32 s49, s49, 0
	s_add_i32 s71, s74, s9
	global_load_lds_dwordx4 v150, s[86:87]
	s_mov_b32 m0, s71
	s_nop 0
	global_load_lds_dwordx4 v148, s[48:49]
	s_add_i32 m0, s71, 0x2000
	s_nop 0
	global_load_lds_dwordx4 v150, s[48:49]
	s_mov_b32 m0, s59
	s_nop 0
	global_load_lds_dwordx4 v247, s[84:85]
	s_mov_b32 m0, s61
	s_nop 0
	global_load_lds_dwordx4 v248, s[84:85]
	s_waitcnt vmcnt(8)
	s_waitcnt lgkmcnt(0)
	s_barrier
	s_setprio 1
	s_waitcnt lgkmcnt(0)
	v_mfma_f32_16x16x32_bf16 v[62:65], v[132:135], v[206:209], v[62:65]
	v_mfma_f32_16x16x32_bf16 v[58:61], v[140:143], v[206:209], v[58:61]
	v_mfma_f32_16x16x32_bf16 v[54:57], v[132:135], v[214:217], v[54:57]
	v_mfma_f32_16x16x32_bf16 v[50:53], v[140:143], v[214:217], v[50:53]
	v_mfma_f32_16x16x32_bf16 v[46:49], v[132:135], v[222:225], v[46:49]
	v_mfma_f32_16x16x32_bf16 v[42:45], v[140:143], v[222:225], v[42:45]
	v_mfma_f32_16x16x32_bf16 v[38:41], v[132:135], v[230:233], v[38:41]
	v_mfma_f32_16x16x32_bf16 v[34:37], v[140:143], v[230:233], v[34:37]
	v_mfma_f32_16x16x32_bf16 v[62:65], v[136:139], v[210:213], v[62:65]
	v_mfma_f32_16x16x32_bf16 v[58:61], v[186:189], v[210:213], v[58:61]
	v_mfma_f32_16x16x32_bf16 v[54:57], v[136:139], v[218:221], v[54:57]
	v_mfma_f32_16x16x32_bf16 v[50:53], v[186:189], v[218:221], v[50:53]
	v_mfma_f32_16x16x32_bf16 v[46:49], v[136:139], v[226:229], v[46:49]
	v_mfma_f32_16x16x32_bf16 v[42:45], v[186:189], v[226:229], v[42:45]
	v_mfma_f32_16x16x32_bf16 v[38:41], v[136:139], v[234:237], v[38:41]
	v_mfma_f32_16x16x32_bf16 v[34:37], v[186:189], v[234:237], v[34:37]
	s_setprio 0
	s_setprio 1
	v_mfma_f32_16x16x32_bf16 v[30:33], v[190:193], v[206:209], v[30:33]
	v_mfma_f32_16x16x32_bf16 v[26:29], v[198:201], v[206:209], v[26:29]
	v_mfma_f32_16x16x32_bf16 v[22:25], v[190:193], v[214:217], v[22:25]
	v_mfma_f32_16x16x32_bf16 v[18:21], v[198:201], v[214:217], v[18:21]
	v_mfma_f32_16x16x32_bf16 v[14:17], v[190:193], v[222:225], v[14:17]
	v_mfma_f32_16x16x32_bf16 v[10:13], v[198:201], v[222:225], v[10:13]
	v_mfma_f32_16x16x32_bf16 v[6:9], v[190:193], v[230:233], v[6:9]
	v_mfma_f32_16x16x32_bf16 v[2:5], v[198:201], v[230:233], v[2:5]
	v_mfma_f32_16x16x32_bf16 v[30:33], v[194:197], v[210:213], v[30:33]
	v_mfma_f32_16x16x32_bf16 v[26:29], v[202:205], v[210:213], v[26:29]
	v_mfma_f32_16x16x32_bf16 v[22:25], v[194:197], v[218:221], v[22:25]
	v_mfma_f32_16x16x32_bf16 v[18:21], v[202:205], v[218:221], v[18:21]
	v_mfma_f32_16x16x32_bf16 v[14:17], v[194:197], v[226:229], v[14:17]
	v_mfma_f32_16x16x32_bf16 v[10:13], v[202:205], v[226:229], v[10:13]
	v_mfma_f32_16x16x32_bf16 v[6:9], v[194:197], v[234:237], v[6:9]
	v_mfma_f32_16x16x32_bf16 v[2:5], v[202:205], v[234:237], v[2:5]
	s_setprio 0
	s_barrier
	s_add_i32 s70, s70, 2
	s_add_u32 s68, s68, 0x100
	s_addc_u32 s69, s69, 0
	s_add_u32 s46, s46, 0x10000
	s_addc_u32 s47, s47, 0
	s_add_u32 s82, s82, 0x10000
	s_addc_u32 s83, s83, 0
	s_mov_b64 s[48:49], 0x10000
	s_cmp_gt_u32 s70, 13
	s_cbranch_scc0 .LBB0_402
	s_and_b64 vcc, exec, s[36:37]
	s_cbranch_vccz .LBB0_405
	s_barrier
